# D queue: own-XCD index popped one unit ahead (atomic latency hidden)
# baseline (speedup 1.0000x reference)
; __device__ __forceinline__ unsigned xb_xcc_id() { return (unsigned)__builtin_amdgcn_s_getreg((3 << 11) | 20) & 0xFu; }
; __global__ void __launch_bounds__(NT, 2) fwd(Args args) {
;     ...
;         for (int r2 = 0; r2 < ((SEQ_P2A & 2) ? 2 : 1); ++r2) for (;;) {
;             __syncthreads();
;             if (tid == 0) { const unsigned myx = xb_xcc_id() & 7u; int got = -1;
;                 for (unsigned k = 0; k < 8u && got < 0; ++k) { const unsigned x = (myx + k) & 7u;
;                     const unsigned v = __hip_atomic_fetch_add(ctl + CW_QD + ((pass * 2 + r2) * 8 + x) * 64, 1u, RLX_AGENT); if (v < 32u) got = (int)(x * 32u + v); }
;                 *slot = got; }
.Ldq_entry:
	v_mov_b32_e32 v224, -1
	s_branch .LBB0_746

; __device__ __forceinline__ unsigned xb_xcc_id() { return (unsigned)__builtin_amdgcn_s_getreg((3 << 11) | 20) & 0xFu; }
; __global__ void __launch_bounds__(NT, 2) fwd(Args args) {
;     ...
;             if (tid == 0) { const unsigned myx = xb_xcc_id() & 7u; int got = -1;
;                 for (unsigned k = 0; k < 8u && got < 0; ++k) { const unsigned x = (myx + k) & 7u;
;                     const unsigned v = __hip_atomic_fetch_add(ctl + CW_QD + ((pass * 2 + r2) * 8 + x) * 64, 1u, RLX_AGENT); if (v < 32u) got = (int)(x * 32u + v); }
;                 *slot = got; }
.LBB0_749:
	s_mov_b64 s[2:3], exec
	v_mbcnt_lo_u32_b32 v3, s2, 0
	s_add_i32 s10, s0, s1
	v_mbcnt_hi_u32_b32 v3, s3, v3
	s_and_b32 s12, s10, 7
	v_cmp_eq_u32_e32 vcc, 0, v3
	s_and_saveexec_b64 s[10:11], vcc
	s_cbranch_execz .LBB0_748
	s_cmp_lg_u32 s1, 0
	s_cbranch_scc1 .Ldq_cold
	v_readfirstlane_b32 s13, v224
	s_cmp_eq_u32 s13, -1
	s_cbranch_scc1 .Ldq_cold
	v_mov_b32_e32 v4, v224
	v_mov_b32_e32 v224, -1
	s_branch .LBB0_748
.Ldq_cold:
	s_lshl_b32 s13, s12, 6
	s_or_b32 s38, s13, s72
	s_lshl_b64 s[14:15], s[38:39], 2
	s_add_u32 s14, s88, s14
	s_addc_u32 s15, s89, s15
	s_bcnt1_i32_b64 s2, s[2:3]
	v_mov_b32_e32 v4, s2
	global_atomic_add v4, v2, v4, s[14:15] sc0
	s_branch .LBB0_748

; #define LAS __attribute__((address_space(3)))
; DI float fexp2(float x) { return __builtin_amdgcn_exp2f(x); }
; __device__ __forceinline__ unsigned xb_xcc_id() { return (unsigned)__builtin_amdgcn_s_getreg((3 << 11) | 20) & 0xFu; }
; DI void unit_dilated2(int u, const bf16* __restrict__ Q, const bf16* __restrict__ K, const bf16* __restrict__ V, const bf16* __restrict__ G, bf16* __restrict__ MIX, LAS unsigned char* lds, int tid, int lane, int wave) {
;     asm volatile("" : "+v"(lane), "+v"(tid));
;     const int bh = u >> 4, blk = u & 15, b = bh >> 3, h = bh & 7, T0 = blk * 512;
;     const int qq = lane & 31, hh = lane >> 5;
;     LAS unsigned char* kst = lds + DL_STAGE + wave * 8192; LAS unsigned char* vst = kst + 4096;
;     LAS float* lseb = (LAS float*)(lds + DL_LSE);
;     const float slope2 = fexp2(-(float)(h + 1)) * LOG2E;
;     DilWT cw = dil_wt(0, wave, b, h, T0, qq, slope2);
;     bf16x8 qf[4];
; #pragma unroll
;     for (int st = 0; st < 4; ++st) qf[st] = *(const bf16x8*)(Q + cw.qrow * 512 + h * 64 + 16 * st + 8 * hh);
;     v4u kr[4], vr[4];
;     dil_load(kr, vr, K, V, cw.rb0 + (long)(32 * 4) * cw.gstride, cw.gstride, lane);
; __global__ void __launch_bounds__(NT, 2) fwd(Args args) {
;     ...
;             if (tid == 0) { const unsigned myx = xb_xcc_id() & 7u; int got = -1;
;                 for (unsigned k = 0; k < 8u && got < 0; ++k) { const unsigned x = (myx + k) & 7u;
;                     const unsigned v = __hip_atomic_fetch_add(ctl + CW_QD + ((pass * 2 + r2) * 8 + x) * 64, 1u, RLX_AGENT); if (v < 32u) got = (int)(x * 32u + v); }
;                 *slot = got; }
;             __syncthreads();
;             const int u = __builtin_amdgcn_readfirstlane(*slot); if (u < 0) break;
.LBB0_752:
	s_or_b64 exec, exec, s[6:7]
	v_mov_b32_e32 v3, s49
	s_waitcnt lgkmcnt(0)
	s_barrier
	ds_read_b32 v3, v3
	s_waitcnt lgkmcnt(0)
	v_readfirstlane_b32 s0, v3
	s_cmp_lt_i32 s0, 0
	s_cbranch_scc1 .LBB0_786
	s_getreg_b32 s2, hwreg(HW_REG_XCC_ID, 0, 4)
	s_and_b32 s2, s2, 7
	s_lshl_b32 s2, s2, 6
	s_or_b32 s2, s2, s72
	s_lshl_b32 s2, s2, 2
	s_add_u32 s6, s88, s2
	s_addc_u32 s7, s89, 0
	s_and_saveexec_b64 s[2:3], s[56:57]
	v_mov_b32_e32 v224, 1
	global_atomic_add v224, v2, v224, s[6:7] sc0
	s_mov_b64 exec, s[2:3]
	s_lshr_b32 s38, s0, 7
	s_bfe_u32 s2, s0, 0x30004
	s_lshl_b32 s0, s0, 9
	s_and_b32 s34, s0, 0x1e00
	s_or_b32 s6, s34, s41
	s_sub_i32 s0, 0x80, s6
	s_lshl_b64 s[12:13], s[38:39], 13
	s_lshr_b32 s7, s0, 5
	s_add_i32 s0, s6, 0xffffff80
	s_add_i32 s3, s2, 1
	s_or_b32 s10, s12, s34
	s_ashr_i32 s1, s0, 31
	v_mov_b32_e32 v3, v182
	v_mov_b32_e32 v227, v0
	s_add_u32 s8, s12, s40
	s_addc_u32 s9, s13, 0
	v_and_b32_e32 v228, 31, v3
	v_or_b32_e32 v4, s41, v228
	s_add_u32 s0, s8, s0
	v_add_u32_e32 v184, s40, v4
	s_mov_b32 s11, s13
	v_mov_b32_e32 v185, v2
	s_addc_u32 s1, s9, s1
	s_lshl_b32 s14, s2, 6
	s_lshl_b32 s38, s2, 7
	v_ashrrev_i32_e32 v14, 5, v3
	v_lshl_add_u64 v[4:5], s[10:11], 0, v[184:185]
	s_cmpk_lt_u32 s6, 0x80
	v_lshlrev_b64 v[4:5], 10, v[4:5]
	v_lshlrev_b32_e32 v6, 3, v14
	s_cselect_b32 s47, s7, 0
	s_lshl_b64 s[16:17], s[0:1], 9
	v_lshl_add_u64 v[4:5], s[78:79], 0, v[4:5]
	v_ashrrev_i32_e32 v7, 31, v6
	s_or_b32 s16, s16, s14
	v_lshl_add_u64 v[4:5], v[4:5], 0, s[38:39]
	v_lshlrev_b64 v[8:9], 1, v[6:7]
	s_add_u32 s0, s16, 0x10000
	v_ashrrev_i32_e32 v186, 3, v3
	v_lshlrev_b32_e32 v7, 3, v3
	v_lshl_add_u64 v[4:5], v[4:5], 0, v[8:9]
	s_addc_u32 s1, s17, 0
	v_and_b32_e32 v188, 56, v7
	v_ashrrev_i32_e32 v187, 31, v186
	global_load_dwordx4 v[114:117], v[4:5], off
	global_load_dwordx4 v[118:121], v[4:5], off offset:32
	global_load_dwordx4 v[122:125], v[4:5], off offset:64
	global_load_dwordx4 v[130:133], v[4:5], off offset:96
	v_or_b32_e32 v4, s0, v188
	v_mov_b32_e32 v5, s1
	v_lshlrev_b64 v[10:11], 9, v[186:187]
	v_lshl_add_u64 v[10:11], v[4:5], 0, v[10:11]
	v_lshlrev_b64 v[10:11], 1, v[10:11]
	v_add_u32_e32 v190, 8, v186
	v_lshl_add_u64 v[12:13], s[76:77], 0, v[10:11]
	v_lshl_add_u64 v[10:11], s[80:81], 0, v[10:11]
	v_ashrrev_i32_e32 v191, 31, v190
	global_load_dwordx4 v[126:129], v[12:13], off
	global_load_dwordx4 v[134:137], v[10:11], off
	v_lshlrev_b64 v[10:11], 9, v[190:191]
	v_lshl_add_u64 v[10:11], v[4:5], 0, v[10:11]
	v_lshlrev_b64 v[10:11], 1, v[10:11]
	v_add_u32_e32 v192, 16, v186
	v_lshl_add_u64 v[12:13], s[76:77], 0, v[10:11]
	v_lshl_add_u64 v[10:11], s[80:81], 0, v[10:11]
	v_ashrrev_i32_e32 v193, 31, v192
	global_load_dwordx4 v[138:141], v[12:13], off
	global_load_dwordx4 v[142:145], v[10:11], off
	v_lshlrev_b64 v[10:11], 9, v[192:193]
	v_lshl_add_u64 v[10:11], v[4:5], 0, v[10:11]
	v_lshlrev_b64 v[10:11], 1, v[10:11]
	v_add_u32_e32 v194, 24, v186
	v_lshl_add_u64 v[12:13], s[76:77], 0, v[10:11]
	v_lshl_add_u64 v[10:11], s[80:81], 0, v[10:11]
	v_ashrrev_i32_e32 v195, 31, v194
	global_load_dwordx4 v[146:149], v[12:13], off
	global_load_dwordx4 v[150:153], v[10:11], off
	v_lshlrev_b64 v[10:11], 9, v[194:195]
	v_lshl_add_u64 v[4:5], v[4:5], 0, v[10:11]
	v_lshlrev_b64 v[4:5], 1, v[4:5]
	v_lshl_add_u64 v[10:11], s[76:77], 0, v[4:5]
	v_lshl_add_u64 v[4:5], s[80:81], 0, v[4:5]
	global_load_dwordx4 v[154:157], v[10:11], off
	global_load_dwordx4 v[158:161], v[4:5], off
	v_cvt_f32_ubyte0_e32 v4, s3
	v_exp_f32_e64 v4, -v4
	v_xor_b32_e32 v5, v186, v3
	v_lshlrev_b32_e32 v5, 4, v5
	s_add_u32 s0, s78, s38
	v_mul_f32_e32 v229, 0x3fb8aa3b, v4
	v_lshlrev_b32_e32 v4, 7, v186
	v_and_or_b32 v4, v5, s50, v4
	v_lshlrev_b32_e32 v5, 2, v14
	v_lshrrev_b32_e32 v13, 2, v3
	s_addc_u32 s1, s79, 0
	v_and_or_b32 v13, v13, 3, v5
	v_lshl_add_u64 v[196:197], s[0:1], 0, v[8:9]
	v_bitop3_b32 v9, v14, v3, 7 bitop3:0x78
	v_add_u32_e32 v10, 2, v14
	v_add_u32_e32 v11, 4, v14
	v_add_u32_e32 v12, 6, v14
	v_lshlrev_b32_e32 v14, 7, v13
	v_and_b32_e32 v7, 8, v7
	v_add3_u32 v7, s73, v14, v7
	v_lshrrev_b32_e32 v14, 3, v3
	v_sub_u32_e32 v230, v5, v228
	v_and_b32_e32 v14, 2, v14
	v_bfe_u32 v15, v3, 1, 1
	v_cvt_f32_i32_e32 v231, v230
	v_or_b32_e32 v16, v14, v15
	v_bitop3_b32 v10, v10, v3, 7 bitop3:0x78
	v_bitop3_b32 v11, v11, v3, 7 bitop3:0x78
	v_bitop3_b32 v12, v12, v3, 7 bitop3:0x78
	v_bitop3_b32 v14, v14, v13, v15 bitop3:0x36
	v_bitop3_b32 v13, v16, v13, 4 bitop3:0x36
	v_lshl_add_u32 v8, v228, 7, s73
	v_lshlrev_b32_e32 v9, 4, v9
	v_lshlrev_b32_e32 v10, 4, v10
	v_lshlrev_b32_e32 v11, 4, v11
	v_lshlrev_b32_e32 v12, 4, v12
	v_lshlrev_b32_e32 v14, 4, v14
	v_lshlrev_b32_e32 v13, 4, v13
	s_mov_b32 s15, s39
	s_mov_b32 s44, 0
	v_mov_b32_e32 v189, v2
	v_sub_u32_e32 v232, v228, v5
	v_add_u32_e32 v233, 0, v6
	v_cmp_gt_u32_e64 s[6:7], 32, v3
	s_mov_b64 s[18:19], 0x200
	v_add_u32_e32 v234, s73, v4
	v_add_u32_e32 v235, v8, v9
	v_add_u32_e32 v236, v8, v10
	v_add_u32_e32 v237, v8, v11
	v_add_u32_e32 v238, v8, v12
	v_add_u32_e32 v239, v7, v14
	v_add_u32_e32 v240, v7, v13
	v_mov_b32_e32 v199, v229
	s_branch .LBB0_755
